# f12 Fourier stages: latent loop rewritten with all stage-1 loads in flight and prefetched stage-2 tables; ctx branch gate loads batched and j-loop software-pipelined by register renaming
# speedup vs baseline: 1.0476x; 1.0142x over previous
.LBB0_304:
	v_and_b32_e32 v74, 3, v207
	v_ashrrev_i32_e32 v75, 2, v207
	v_lshlrev_b32_e32 v128, 8, v74
	v_lshl_add_u32 v76, v75, 6, v250
	v_lshl_add_u64 v[78:79], v[68:69], 0, v[128:129]
	v_mad_i64_i32 v[66:67], s[0:1], v76, s2, v[78:79]
	v_or_b32_e32 v77, 32, v76
	v_mad_i64_i32 v[64:65], s[0:1], v77, s2, v[78:79]
	s_mov_b64 s[0:1], 0x1000
	v_lshl_add_u64 v[84:85], v[70:71], 0, s[0:1]
	v_lshl_add_u64 v[86:87], v[70:71], 0, s[20:21]
	s_mov_b64 s[0:1], 0x3000
	v_lshl_add_u64 v[88:89], v[70:71], 0, s[0:1]
	global_load_dwordx4 v[166:169], v[70:71], off
	global_load_dwordx4 v[208:211], v[86:87], off
	global_load_dwordx4 v[100:103], v[66:67], off
	global_load_dwordx4 v[136:139], v[64:65], off
	global_load_dwordx4 v[170:173], v[70:71], off offset:1024
	global_load_dwordx4 v[212:215], v[86:87], off offset:1024
	global_load_dwordx4 v[104:107], v[66:67], off offset:32
	global_load_dwordx4 v[140:143], v[64:65], off offset:32
	global_load_dwordx4 v[174:177], v[70:71], off offset:2048
	global_load_dwordx4 v[216:219], v[86:87], off offset:2048
	global_load_dwordx4 v[108:111], v[66:67], off offset:64
	global_load_dwordx4 v[144:147], v[64:65], off offset:64
	global_load_dwordx4 v[178:181], v[70:71], off offset:3072
	global_load_dwordx4 v[220:223], v[86:87], off offset:3072
	global_load_dwordx4 v[112:115], v[66:67], off offset:96
	global_load_dwordx4 v[148:151], v[64:65], off offset:96
	global_load_dwordx4 v[182:185], v[84:85], off
	global_load_dwordx4 v[224:227], v[88:89], off
	global_load_dwordx4 v[116:119], v[66:67], off offset:128
	global_load_dwordx4 v[152:155], v[64:65], off offset:128
	global_load_dwordx4 v[186:189], v[84:85], off offset:1024
	global_load_dwordx4 v[228:231], v[88:89], off offset:1024
	global_load_dwordx4 v[120:123], v[66:67], off offset:160
	global_load_dwordx4 v[156:159], v[64:65], off offset:160
	global_load_dwordx4 v[190:193], v[84:85], off offset:2048
	global_load_dwordx4 v[236:239], v[88:89], off offset:2048
	global_load_dwordx4 v[124:127], v[66:67], off offset:192
	global_load_dwordx4 v[160:163], v[64:65], off offset:192
	global_load_dwordx4 v[194:197], v[84:85], off offset:3072
	global_load_dwordx4 v[240:243], v[88:89], off offset:3072
	global_load_dwordx4 v[132:135], v[66:67], off offset:224
	global_load_dwordx4 v[198:201], v[64:65], off offset:224
	v_ashrrev_i32_e32 v80, 5, v207
	v_bfi_b32 v80, -4, v80, v207
	v_ashrrev_i32_e32 v81, 31, v80
	v_lshlrev_b64 v[80:81], 20, v[80:81]
	v_lshlrev_b32_e32 v82, 14, v75
	v_and_b32_e32 v128, 0x7c000, v82
	v_lshl_add_u64 v[80:81], v[96:97], 0, v[80:81]
	v_lshl_add_u64 v[80:81], v[80:81], 0, v[128:129]
	v_mov_b32_e32 v165, v129
	v_lshl_add_u64 v[92:93], v[80:81], 0, v[164:165]
	v_add_u32_e32 v207, s92, v207
	v_cmp_lt_i32_e32 vcc, s91, v207
	s_or_b64 s[10:11], vcc, s[10:11]
	s_waitcnt vmcnt(28)
	v_mfma_f32_32x32x16_bf16 v[48:63], v[100:103], v[166:169], 0
	v_mfma_f32_32x32x16_bf16 v[32:47], v[100:103], v[208:211], 0
	v_mfma_f32_32x32x16_bf16 v[16:31], v[136:139], v[166:169], 0
	v_mfma_f32_32x32x16_bf16 v[0:15], v[136:139], v[208:211], 0
	s_waitcnt vmcnt(24)
	v_mfma_f32_32x32x16_bf16 v[48:63], v[104:107], v[170:173], v[48:63]
	v_mfma_f32_32x32x16_bf16 v[32:47], v[104:107], v[212:215], v[32:47]
	v_mfma_f32_32x32x16_bf16 v[16:31], v[140:143], v[170:173], v[16:31]
	v_mfma_f32_32x32x16_bf16 v[0:15], v[140:143], v[212:215], v[0:15]
	s_waitcnt vmcnt(20)
	v_mfma_f32_32x32x16_bf16 v[48:63], v[108:111], v[174:177], v[48:63]
	v_mfma_f32_32x32x16_bf16 v[32:47], v[108:111], v[216:219], v[32:47]
	v_mfma_f32_32x32x16_bf16 v[16:31], v[144:147], v[174:177], v[16:31]
	v_mfma_f32_32x32x16_bf16 v[0:15], v[144:147], v[216:219], v[0:15]
	s_waitcnt vmcnt(16)
	v_mfma_f32_32x32x16_bf16 v[48:63], v[112:115], v[178:181], v[48:63]
	v_mfma_f32_32x32x16_bf16 v[32:47], v[112:115], v[220:223], v[32:47]
	v_mfma_f32_32x32x16_bf16 v[16:31], v[148:151], v[178:181], v[16:31]
	v_mfma_f32_32x32x16_bf16 v[0:15], v[148:151], v[220:223], v[0:15]
	s_waitcnt vmcnt(12)
	v_mfma_f32_32x32x16_bf16 v[48:63], v[116:119], v[182:185], v[48:63]
	v_mfma_f32_32x32x16_bf16 v[32:47], v[116:119], v[224:227], v[32:47]
	v_mfma_f32_32x32x16_bf16 v[16:31], v[152:155], v[182:185], v[16:31]
	v_mfma_f32_32x32x16_bf16 v[0:15], v[152:155], v[224:227], v[0:15]
	s_waitcnt vmcnt(8)
	v_mfma_f32_32x32x16_bf16 v[48:63], v[120:123], v[186:189], v[48:63]
	v_mfma_f32_32x32x16_bf16 v[32:47], v[120:123], v[228:231], v[32:47]
	v_mfma_f32_32x32x16_bf16 v[16:31], v[156:159], v[186:189], v[16:31]
	v_mfma_f32_32x32x16_bf16 v[0:15], v[156:159], v[228:231], v[0:15]
	s_waitcnt vmcnt(4)
	v_mfma_f32_32x32x16_bf16 v[48:63], v[124:127], v[190:193], v[48:63]
	v_mfma_f32_32x32x16_bf16 v[32:47], v[124:127], v[236:239], v[32:47]
	v_mfma_f32_32x32x16_bf16 v[16:31], v[160:163], v[190:193], v[16:31]
	v_mfma_f32_32x32x16_bf16 v[0:15], v[160:163], v[236:239], v[0:15]
	s_waitcnt vmcnt(0)
	v_mfma_f32_32x32x16_bf16 v[48:63], v[132:135], v[194:197], v[48:63]
	v_mfma_f32_32x32x16_bf16 v[32:47], v[132:135], v[240:243], v[32:47]
	v_mfma_f32_32x32x16_bf16 v[16:31], v[198:201], v[194:197], v[16:31]
	v_mfma_f32_32x32x16_bf16 v[0:15], v[198:201], v[240:243], v[0:15]
	v_mov_b64_e32 v[90:91], v[98:99]
	global_load_dwordx4 v[100:103], v[90:91], off
	global_load_dwordx4 v[104:107], v[90:91], off offset:1024
	global_load_dwordx4 v[108:111], v[90:91], off offset:2048
	global_load_dwordx4 v[112:115], v[90:91], off offset:3072
	s_mov_b64 s[0:1], 0x1000
	v_lshl_add_u64 v[90:91], v[98:99], 0, s[0:1]
	global_load_dwordx4 v[116:119], v[90:91], off
	global_load_dwordx4 v[120:123], v[90:91], off offset:1024
	global_load_dwordx4 v[124:127], v[90:91], off offset:2048
	global_load_dwordx4 v[132:135], v[90:91], off offset:3072
	s_mov_b64 s[0:1], 0x2000
	v_lshl_add_u64 v[90:91], v[98:99], 0, s[0:1]
	global_load_dwordx4 v[136:139], v[90:91], off
	global_load_dwordx4 v[140:143], v[90:91], off offset:1024
	global_load_dwordx4 v[144:147], v[90:91], off offset:2048
	global_load_dwordx4 v[148:151], v[90:91], off offset:3072
	s_mov_b64 s[0:1], 0x3000
	v_lshl_add_u64 v[90:91], v[98:99], 0, s[0:1]
	global_load_dwordx4 v[152:155], v[90:91], off
	global_load_dwordx4 v[156:159], v[90:91], off offset:1024
	global_load_dwordx4 v[160:163], v[90:91], off offset:2048
	global_load_dwordx4 v[198:201], v[90:91], off offset:3072
	v_cvt_pk_bf16_f32 v166, v48, v49
	v_cvt_pk_bf16_f32 v167, v50, v51
	v_cvt_pk_bf16_f32 v168, v52, v53
	v_cvt_pk_bf16_f32 v169, v54, v55
	v_cvt_pk_bf16_f32 v170, v56, v57
	v_cvt_pk_bf16_f32 v171, v58, v59
	v_cvt_pk_bf16_f32 v172, v60, v61
	v_cvt_pk_bf16_f32 v173, v62, v63
	v_cvt_pk_bf16_f32 v174, v16, v17
	v_cvt_pk_bf16_f32 v175, v18, v19
	v_cvt_pk_bf16_f32 v176, v20, v21
	v_cvt_pk_bf16_f32 v177, v22, v23
	v_cvt_pk_bf16_f32 v178, v24, v25
	v_cvt_pk_bf16_f32 v179, v26, v27
	v_cvt_pk_bf16_f32 v180, v28, v29
	v_cvt_pk_bf16_f32 v181, v30, v31
	v_cvt_pk_bf16_f32 v182, v32, v33
	v_cvt_pk_bf16_f32 v183, v34, v35
	v_cvt_pk_bf16_f32 v184, v36, v37
	v_cvt_pk_bf16_f32 v185, v38, v39
	v_cvt_pk_bf16_f32 v186, v40, v41
	v_cvt_pk_bf16_f32 v187, v42, v43
	v_cvt_pk_bf16_f32 v188, v44, v45
	v_cvt_pk_bf16_f32 v189, v46, v47
	v_cvt_pk_bf16_f32 v190, v0, v1
	v_cvt_pk_bf16_f32 v191, v2, v3
	v_cvt_pk_bf16_f32 v192, v4, v5
	v_cvt_pk_bf16_f32 v193, v6, v7
	v_cvt_pk_bf16_f32 v194, v8, v9
	v_cvt_pk_bf16_f32 v195, v10, v11
	v_cvt_pk_bf16_f32 v196, v12, v13
	v_cvt_pk_bf16_f32 v197, v14, v15
	s_mov_b64 s[0:1], 0x4000
	v_lshl_add_u64 v[90:91], v[98:99], 0, s[0:1]
	global_load_dwordx4 v[208:211], v[90:91], off
	global_load_dwordx4 v[212:215], v[90:91], off offset:1024
	global_load_dwordx4 v[216:219], v[90:91], off offset:2048
	global_load_dwordx4 v[220:223], v[90:91], off offset:3072
	s_mov_b64 s[0:1], 0x5000
	v_lshl_add_u64 v[90:91], v[98:99], 0, s[0:1]
	global_load_dwordx4 v[224:227], v[90:91], off
	global_load_dwordx4 v[228:231], v[90:91], off offset:1024
	global_load_dwordx4 v[236:239], v[90:91], off offset:2048
	global_load_dwordx4 v[240:243], v[90:91], off offset:3072
	s_mov_b64 s[0:1], 0x6000
	v_lshl_add_u64 v[90:91], v[98:99], 0, s[0:1]
	global_load_dwordx4 v[16:19], v[90:91], off
	global_load_dwordx4 v[20:23], v[90:91], off offset:1024
	global_load_dwordx4 v[24:27], v[90:91], off offset:2048
	global_load_dwordx4 v[28:31], v[90:91], off offset:3072
	s_mov_b64 s[0:1], 0x7000
	v_lshl_add_u64 v[90:91], v[98:99], 0, s[0:1]
	global_load_dwordx4 v[32:35], v[90:91], off
	global_load_dwordx4 v[36:39], v[90:91], off offset:1024
	global_load_dwordx4 v[40:43], v[90:91], off offset:2048
	global_load_dwordx4 v[44:47], v[90:91], off offset:3072
	s_waitcnt vmcnt(24)
	v_mfma_f32_32x32x16_bf16 v[0:15], v[100:103], v[166:169], 0
	v_mfma_f32_32x32x16_bf16 v[0:15], v[104:107], v[170:173], v[0:15]
	v_mfma_f32_32x32x16_bf16 v[0:15], v[108:111], v[174:177], v[0:15]
	v_mfma_f32_32x32x16_bf16 v[0:15], v[112:115], v[178:181], v[0:15]
	v_mfma_f32_32x32x16_bf16 v[0:15], v[116:119], v[182:185], v[0:15]
	v_mfma_f32_32x32x16_bf16 v[0:15], v[120:123], v[186:189], v[0:15]
	v_mfma_f32_32x32x16_bf16 v[0:15], v[124:127], v[190:193], v[0:15]
	v_mfma_f32_32x32x16_bf16 v[0:15], v[132:135], v[194:197], v[0:15]
	s_waitcnt vmcnt(16)
	v_mfma_f32_32x32x16_bf16 v[48:63], v[136:139], v[166:169], 0
	v_mfma_f32_32x32x16_bf16 v[48:63], v[140:143], v[170:173], v[48:63]
	v_mfma_f32_32x32x16_bf16 v[48:63], v[144:147], v[174:177], v[48:63]
	v_mfma_f32_32x32x16_bf16 v[48:63], v[148:151], v[178:181], v[48:63]
	v_mfma_f32_32x32x16_bf16 v[48:63], v[152:155], v[182:185], v[48:63]
	v_mfma_f32_32x32x16_bf16 v[48:63], v[156:159], v[186:189], v[48:63]
	v_mfma_f32_32x32x16_bf16 v[48:63], v[160:163], v[190:193], v[48:63]
	v_mfma_f32_32x32x16_bf16 v[48:63], v[198:201], v[194:197], v[48:63]
	s_nop 1
	v_mov_b64_e32 v[76:77], v[92:93]
	s_mov_b64 s[0:1], 0x1000
	v_lshl_add_u64 v[78:79], v[76:77], 0, s[0:1]
	v_cvt_pk_bf16_f32 v82, v0, v1
	global_store_short v[76:77], v82, off
	global_store_short_d16_hi v[76:77], v82, off offset:256
	v_cvt_pk_bf16_f32 v83, v2, v3
	global_store_short v[76:77], v83, off offset:512
	global_store_short_d16_hi v[76:77], v83, off offset:768
	v_cvt_pk_bf16_f32 v84, v4, v5
	global_store_short v[76:77], v84, off offset:2048
	global_store_short_d16_hi v[76:77], v84, off offset:2304
	v_cvt_pk_bf16_f32 v85, v6, v7
	global_store_short v[76:77], v85, off offset:2560
	global_store_short_d16_hi v[76:77], v85, off offset:2816
	v_cvt_pk_bf16_f32 v82, v8, v9
	global_store_short v[78:79], v82, off
	global_store_short_d16_hi v[78:79], v82, off offset:256
	v_cvt_pk_bf16_f32 v83, v10, v11
	global_store_short v[78:79], v83, off offset:512
	global_store_short_d16_hi v[78:79], v83, off offset:768
	v_cvt_pk_bf16_f32 v84, v12, v13
	global_store_short v[78:79], v84, off offset:2048
	global_store_short_d16_hi v[78:79], v84, off offset:2304
	v_cvt_pk_bf16_f32 v85, v14, v15
	global_store_short v[78:79], v85, off offset:2560
	global_store_short_d16_hi v[78:79], v85, off offset:2816
	s_waitcnt vmcnt(24)
	v_mfma_f32_32x32x16_bf16 v[0:15], v[208:211], v[166:169], 0
	v_mfma_f32_32x32x16_bf16 v[0:15], v[212:215], v[170:173], v[0:15]
	v_mfma_f32_32x32x16_bf16 v[0:15], v[216:219], v[174:177], v[0:15]
	v_mfma_f32_32x32x16_bf16 v[0:15], v[220:223], v[178:181], v[0:15]
	v_mfma_f32_32x32x16_bf16 v[0:15], v[224:227], v[182:185], v[0:15]
	v_mfma_f32_32x32x16_bf16 v[0:15], v[228:231], v[186:189], v[0:15]
	v_mfma_f32_32x32x16_bf16 v[0:15], v[236:239], v[190:193], v[0:15]
	v_mfma_f32_32x32x16_bf16 v[0:15], v[240:243], v[194:197], v[0:15]
	s_nop 1
	s_mov_b64 s[0:1], 0x2000
	v_lshl_add_u64 v[76:77], v[92:93], 0, s[0:1]
	s_mov_b64 s[0:1], 0x1000
	v_lshl_add_u64 v[78:79], v[76:77], 0, s[0:1]
	v_cvt_pk_bf16_f32 v82, v48, v49
	global_store_short v[76:77], v82, off
	global_store_short_d16_hi v[76:77], v82, off offset:256
	v_cvt_pk_bf16_f32 v83, v50, v51
	global_store_short v[76:77], v83, off offset:512
	global_store_short_d16_hi v[76:77], v83, off offset:768
	v_cvt_pk_bf16_f32 v84, v52, v53
	global_store_short v[76:77], v84, off offset:2048
	global_store_short_d16_hi v[76:77], v84, off offset:2304
	v_cvt_pk_bf16_f32 v85, v54, v55
	global_store_short v[76:77], v85, off offset:2560
	global_store_short_d16_hi v[76:77], v85, off offset:2816
	v_cvt_pk_bf16_f32 v82, v56, v57
	global_store_short v[78:79], v82, off
	global_store_short_d16_hi v[78:79], v82, off offset:256
	v_cvt_pk_bf16_f32 v83, v58, v59
	global_store_short v[78:79], v83, off offset:512
	global_store_short_d16_hi v[78:79], v83, off offset:768
	v_cvt_pk_bf16_f32 v84, v60, v61
	global_store_short v[78:79], v84, off offset:2048
	global_store_short_d16_hi v[78:79], v84, off offset:2304
	v_cvt_pk_bf16_f32 v85, v62, v63
	global_store_short v[78:79], v85, off offset:2560
	global_store_short_d16_hi v[78:79], v85, off offset:2816
	s_waitcnt vmcnt(32)
	v_mfma_f32_32x32x16_bf16 v[48:63], v[16:19], v[166:169], 0
	v_mfma_f32_32x32x16_bf16 v[48:63], v[20:23], v[170:173], v[48:63]
	v_mfma_f32_32x32x16_bf16 v[48:63], v[24:27], v[174:177], v[48:63]
	v_mfma_f32_32x32x16_bf16 v[48:63], v[28:31], v[178:181], v[48:63]
	v_mfma_f32_32x32x16_bf16 v[48:63], v[32:35], v[182:185], v[48:63]
	v_mfma_f32_32x32x16_bf16 v[48:63], v[36:39], v[186:189], v[48:63]
	v_mfma_f32_32x32x16_bf16 v[48:63], v[40:43], v[190:193], v[48:63]
	v_mfma_f32_32x32x16_bf16 v[48:63], v[44:47], v[194:197], v[48:63]
	s_nop 1
	s_mov_b64 s[0:1], 0x80000
	v_lshl_add_u64 v[76:77], v[92:93], 0, s[0:1]
	s_mov_b64 s[0:1], 0x1000
	v_lshl_add_u64 v[78:79], v[76:77], 0, s[0:1]
	v_cvt_pk_bf16_f32 v82, v0, v1
	global_store_short v[76:77], v82, off
	global_store_short_d16_hi v[76:77], v82, off offset:256
	v_cvt_pk_bf16_f32 v83, v2, v3
	global_store_short v[76:77], v83, off offset:512
	global_store_short_d16_hi v[76:77], v83, off offset:768
	v_cvt_pk_bf16_f32 v84, v4, v5
	global_store_short v[76:77], v84, off offset:2048
	global_store_short_d16_hi v[76:77], v84, off offset:2304
	v_cvt_pk_bf16_f32 v85, v6, v7
	global_store_short v[76:77], v85, off offset:2560
	global_store_short_d16_hi v[76:77], v85, off offset:2816
	v_cvt_pk_bf16_f32 v82, v8, v9
	global_store_short v[78:79], v82, off
	global_store_short_d16_hi v[78:79], v82, off offset:256
	v_cvt_pk_bf16_f32 v83, v10, v11
	global_store_short v[78:79], v83, off offset:512
	global_store_short_d16_hi v[78:79], v83, off offset:768
	v_cvt_pk_bf16_f32 v84, v12, v13
	global_store_short v[78:79], v84, off offset:2048
	global_store_short_d16_hi v[78:79], v84, off offset:2304
	v_cvt_pk_bf16_f32 v85, v14, v15
	global_store_short v[78:79], v85, off offset:2560
	global_store_short_d16_hi v[78:79], v85, off offset:2816
	s_nop 7
	s_nop 3
	s_mov_b64 s[0:1], 0x82000
	v_lshl_add_u64 v[76:77], v[92:93], 0, s[0:1]
	s_mov_b64 s[0:1], 0x1000
	v_lshl_add_u64 v[78:79], v[76:77], 0, s[0:1]
	v_cvt_pk_bf16_f32 v82, v48, v49
	global_store_short v[76:77], v82, off
	global_store_short_d16_hi v[76:77], v82, off offset:256
	v_cvt_pk_bf16_f32 v83, v50, v51
	global_store_short v[76:77], v83, off offset:512
	global_store_short_d16_hi v[76:77], v83, off offset:768
	v_cvt_pk_bf16_f32 v84, v52, v53
	global_store_short v[76:77], v84, off offset:2048
	global_store_short_d16_hi v[76:77], v84, off offset:2304
	v_cvt_pk_bf16_f32 v85, v54, v55
	global_store_short v[76:77], v85, off offset:2560
	global_store_short_d16_hi v[76:77], v85, off offset:2816
	v_cvt_pk_bf16_f32 v82, v56, v57
	global_store_short v[78:79], v82, off
	global_store_short_d16_hi v[78:79], v82, off offset:256
	v_cvt_pk_bf16_f32 v83, v58, v59
	global_store_short v[78:79], v83, off offset:512
	global_store_short_d16_hi v[78:79], v83, off offset:768
	v_cvt_pk_bf16_f32 v84, v60, v61
	global_store_short v[78:79], v84, off offset:2048
	global_store_short_d16_hi v[78:79], v84, off offset:2304
	v_cvt_pk_bf16_f32 v85, v62, v63
	global_store_short v[78:79], v85, off offset:2560
	global_store_short_d16_hi v[78:79], v85, off offset:2816
	s_andn2_b64 exec, exec, s[10:11]
	s_cbranch_execnz .LBB0_304

.LBB0_308:
	v_add_u32_e32 v32, 32, v131
	v_mad_i64_i32 v[160:161], s[2:3], v131, s1, v[100:101]
	v_mad_i64_i32 v[162:163], s[2:3], v32, s1, v[100:101]
	global_load_dwordx4 v[32:35], v[102:103], off
	global_load_dwordx4 v[96:99], v[102:103], off offset:1024
	global_load_dwordx4 v[36:39], v[104:105], off
	global_load_dwordx4 v[132:135], v[106:107], off
	global_load_dwordx4 v[40:43], v[160:161], off
	global_load_dwordx4 v[136:139], v[160:161], off offset:32
	global_load_dwordx4 v[44:47], v[162:163], off
	global_load_dwordx4 v[140:143], v[162:163], off offset:32
	global_load_dwordx4 v[168:171], v[102:103], off offset:2048
	global_load_dwordx4 v[172:175], v[102:103], off offset:3072
	global_load_dwordx4 v[176:179], v[108:109], off
	global_load_dwordx4 v[180:183], v[110:111], off
	global_load_dwordx4 v[184:187], v[160:161], off offset:64
	global_load_dwordx4 v[188:191], v[160:161], off offset:96
	global_load_dwordx4 v[192:195], v[162:163], off offset:64
	global_load_dwordx4 v[196:199], v[162:163], off offset:96
	s_waitcnt vmcnt(8)
	v_mfma_f32_32x32x16_bf16 v[80:95], v[40:43], v[32:35], 0
	v_mfma_f32_32x32x16_bf16 v[64:79], v[40:43], v[36:39], 0
	v_mfma_f32_32x32x16_bf16 v[48:63], v[44:47], v[32:35], 0
	v_mfma_f32_32x32x16_bf16 v[32:47], v[44:47], v[36:39], 0
	v_mfma_f32_32x32x16_bf16 v[80:95], v[136:139], v[96:99], v[80:95]
	v_mfma_f32_32x32x16_bf16 v[64:79], v[136:139], v[132:135], v[64:79]
	v_mfma_f32_32x32x16_bf16 v[48:63], v[140:143], v[96:99], v[48:63]
	v_mfma_f32_32x32x16_bf16 v[32:47], v[140:143], v[132:135], v[32:47]
	global_load_dwordx4 v[96:99], v[112:113], off
	global_load_dwordx4 v[132:135], v[114:115], off
	global_load_dwordx4 v[136:139], v[116:117], off
	global_load_dwordx4 v[140:143], v[118:119], off
	global_load_dwordx4 v[144:147], v[160:161], off offset:128
	global_load_dwordx4 v[148:151], v[160:161], off offset:160
	global_load_dwordx4 v[152:155], v[162:163], off offset:128
	global_load_dwordx4 v[156:159], v[162:163], off offset:160
	s_waitcnt vmcnt(8)
	v_mfma_f32_32x32x16_bf16 v[80:95], v[184:187], v[168:171], v[80:95]
	v_mfma_f32_32x32x16_bf16 v[64:79], v[184:187], v[176:179], v[64:79]
	v_mfma_f32_32x32x16_bf16 v[48:63], v[192:195], v[168:171], v[48:63]
	v_mfma_f32_32x32x16_bf16 v[32:47], v[192:195], v[176:179], v[32:47]
	v_mfma_f32_32x32x16_bf16 v[80:95], v[188:191], v[172:175], v[80:95]
	v_mfma_f32_32x32x16_bf16 v[64:79], v[188:191], v[180:183], v[64:79]
	v_mfma_f32_32x32x16_bf16 v[48:63], v[196:199], v[172:175], v[48:63]
	v_mfma_f32_32x32x16_bf16 v[32:47], v[196:199], v[180:183], v[32:47]
	global_load_dwordx4 v[168:171], v[120:121], off
	global_load_dwordx4 v[172:175], v[122:123], off
	global_load_dwordx4 v[176:179], v[124:125], off
	global_load_dwordx4 v[180:183], v[126:127], off
	global_load_dwordx4 v[184:187], v[160:161], off offset:192
	global_load_dwordx4 v[188:191], v[160:161], off offset:224
	global_load_dwordx4 v[192:195], v[162:163], off offset:192
	global_load_dwordx4 v[196:199], v[162:163], off offset:224
	s_waitcnt vmcnt(8)
	v_mfma_f32_32x32x16_bf16 v[80:95], v[144:147], v[96:99], v[80:95]
	v_mfma_f32_32x32x16_bf16 v[64:79], v[144:147], v[132:135], v[64:79]
	v_mfma_f32_32x32x16_bf16 v[48:63], v[152:155], v[96:99], v[48:63]
	v_mfma_f32_32x32x16_bf16 v[32:47], v[152:155], v[132:135], v[32:47]
	v_mfma_f32_32x32x16_bf16 v[80:95], v[148:151], v[136:139], v[80:95]
	v_mfma_f32_32x32x16_bf16 v[64:79], v[148:151], v[140:143], v[64:79]
	v_mfma_f32_32x32x16_bf16 v[48:63], v[156:159], v[136:139], v[48:63]
	v_mfma_f32_32x32x16_bf16 v[32:47], v[156:159], v[140:143], v[32:47]
	s_waitcnt vmcnt(0)
	v_mfma_f32_32x32x16_bf16 v[80:95], v[184:187], v[168:171], v[80:95]
	v_mfma_f32_32x32x16_bf16 v[64:79], v[184:187], v[172:175], v[64:79]
	v_mfma_f32_32x32x16_bf16 v[48:63], v[192:195], v[168:171], v[48:63]
	v_mfma_f32_32x32x16_bf16 v[32:47], v[192:195], v[172:175], v[32:47]
	v_mfma_f32_32x32x16_bf16 v[80:95], v[188:191], v[176:179], v[80:95]
	v_mfma_f32_32x32x16_bf16 v[64:79], v[188:191], v[180:183], v[64:79]
	v_mfma_f32_32x32x16_bf16 v[48:63], v[196:199], v[176:179], v[48:63]
	v_mfma_f32_32x32x16_bf16 v[32:47], v[196:199], v[180:183], v[32:47]
	s_nop 8
	v_cvt_pk_bf16_f32 v97, v82, v83
	v_cvt_pk_bf16_f32 v82, v92, v93
	v_add_u32_e32 v92, s0, v128
	v_cvt_pk_bf16_f32 v96, v80, v81
	v_cvt_pk_bf16_f32 v98, v84, v85
	v_cvt_pk_bf16_f32 v99, v86, v87
	v_cvt_pk_bf16_f32 v80, v88, v89
	v_cvt_pk_bf16_f32 v84, v64, v65
	v_cvt_pk_bf16_f32 v85, v66, v67
	v_cvt_pk_bf16_f32 v86, v68, v69
	v_cvt_pk_bf16_f32 v87, v70, v71
	v_cvt_pk_bf16_f32 v64, v72, v73
	v_cvt_pk_bf16_f32 v66, v76, v77
	v_cvt_pk_bf16_f32 v68, v48, v49
	v_cvt_pk_bf16_f32 v69, v50, v51
	v_cvt_pk_bf16_f32 v70, v52, v53
	v_cvt_pk_bf16_f32 v71, v54, v55
	v_cvt_pk_bf16_f32 v48, v56, v57
	v_cvt_pk_bf16_f32 v50, v60, v61
	v_cvt_pk_bf16_f32 v52, v32, v33
	v_cvt_pk_bf16_f32 v53, v34, v35
	v_cvt_pk_bf16_f32 v54, v36, v37
	v_cvt_pk_bf16_f32 v32, v40, v41
	v_cvt_pk_bf16_f32 v34, v44, v45
	v_add_u32_e32 v36, 0x1800, v92
	v_add_u32_e32 v40, 0x1c00, v92
	v_add_u32_e32 v44, 0x1840, v92
	v_add_u32_e32 v56, 0x1c40, v92
	v_add_u32_e32 v60, 0x1880, v92
	v_add_u32_e32 v72, 0x1c80, v92
	v_add_u32_e32 v76, 0x18c0, v92
	v_add_u32_e32 v88, 0x1cc0, v92
	v_ashrrev_i32_e32 v37, 31, v36
	v_ashrrev_i32_e32 v41, 31, v40
	v_ashrrev_i32_e32 v45, 31, v44
	v_ashrrev_i32_e32 v57, 31, v56
	v_ashrrev_i32_e32 v61, 31, v60
	v_ashrrev_i32_e32 v73, 31, v72
	v_ashrrev_i32_e32 v77, 31, v76
	v_ashrrev_i32_e32 v89, 31, v88
	v_lshl_add_u64 v[36:37], v[36:37], 4, s[12:13]
	v_lshl_add_u64 v[40:41], v[40:41], 4, s[12:13]
	v_lshl_add_u64 v[44:45], v[44:45], 4, s[12:13]
	v_lshl_add_u64 v[56:57], v[56:57], 4, s[12:13]
	v_lshl_add_u64 v[60:61], v[60:61], 4, s[12:13]
	v_lshl_add_u64 v[72:73], v[72:73], 4, s[12:13]
	v_lshl_add_u64 v[76:77], v[76:77], 4, s[12:13]
	v_lshl_add_u64 v[88:89], v[88:89], 4, s[12:13]
	v_cvt_pk_bf16_f32 v81, v90, v91
	v_cvt_pk_bf16_f32 v65, v74, v75
	v_cvt_pk_bf16_f32 v67, v78, v79
	v_cvt_pk_bf16_f32 v49, v58, v59
	v_cvt_pk_bf16_f32 v51, v62, v63
	v_cvt_pk_bf16_f32 v55, v38, v39
	v_cvt_pk_bf16_f32 v33, v42, v43
	v_cvt_pk_bf16_f32 v35, v46, v47
	global_load_dwordx4 v[36:39], v[36:37], off
	v_cvt_pk_bf16_f32 v83, v94, v95
	global_load_dwordx4 v[40:43], v[40:41], off
	s_nop 0
	global_load_dwordx4 v[44:47], v[44:45], off
	s_nop 0
	global_load_dwordx4 v[56:59], v[56:57], off
	s_nop 0
	global_load_dwordx4 v[60:63], v[60:61], off
	s_nop 0
	global_load_dwordx4 v[72:75], v[72:73], off
	s_nop 0
	global_load_dwordx4 v[76:79], v[76:77], off
	s_nop 0
	global_load_dwordx4 v[88:91], v[88:89], off
	v_add_u32_e32 v208, 0x2000, v92
	v_add_u32_e32 v210, 0x2400, v92
	v_add_u32_e32 v214, 0x2040, v92
	v_add_u32_e32 v216, 0x2440, v92
	v_add_u32_e32 v220, 0x2080, v92
	v_add_u32_e32 v222, 0x2480, v92
	v_add_u32_e32 v226, 0x20c0, v92
	v_add_u32_e32 v228, 0x24c0, v92
	v_ashrrev_i32_e32 v209, 31, v208
	v_ashrrev_i32_e32 v211, 31, v210
	v_ashrrev_i32_e32 v215, 31, v214
	v_ashrrev_i32_e32 v217, 31, v216
	v_ashrrev_i32_e32 v221, 31, v220
	v_ashrrev_i32_e32 v223, 31, v222
	v_ashrrev_i32_e32 v227, 31, v226
	v_ashrrev_i32_e32 v229, 31, v228
	v_lshl_add_u64 v[208:209], v[208:209], 4, s[12:13]
	v_lshl_add_u64 v[212:213], v[210:211], 4, s[12:13]
	v_lshl_add_u64 v[214:215], v[214:215], 4, s[12:13]
	v_lshl_add_u64 v[218:219], v[216:217], 4, s[12:13]
	v_lshl_add_u64 v[220:221], v[220:221], 4, s[12:13]
	v_lshl_add_u64 v[224:225], v[222:223], 4, s[12:13]
	v_lshl_add_u64 v[226:227], v[226:227], 4, s[12:13]
	v_lshl_add_u64 v[230:231], v[228:229], 4, s[12:13]
	global_load_dwordx4 v[168:171], v[208:209], off
	global_load_dwordx4 v[172:175], v[212:213], off
	global_load_dwordx4 v[176:179], v[214:215], off
	global_load_dwordx4 v[180:183], v[218:219], off
	global_load_dwordx4 v[184:187], v[220:221], off
	global_load_dwordx4 v[188:191], v[224:225], off
	global_load_dwordx4 v[192:195], v[226:227], off
	global_load_dwordx4 v[196:199], v[230:231], off
	s_waitcnt vmcnt(8)
	v_mfma_f32_32x32x16_bf16 v[16:31], v[36:39], v[96:99], v[16:31]
	v_mfma_f32_32x32x16_bf16 v[16:31], v[40:43], v[84:87], v[16:31]
	v_mfma_f32_32x32x16_bf16 v[16:31], v[44:47], v[80:83], v[16:31]
	v_mfma_f32_32x32x16_bf16 v[16:31], v[56:59], v[64:67], v[16:31]
	v_mfma_f32_32x32x16_bf16 v[16:31], v[60:63], v[68:71], v[16:31]
	v_mfma_f32_32x32x16_bf16 v[16:31], v[72:75], v[52:55], v[16:31]
	v_mfma_f32_32x32x16_bf16 v[16:31], v[76:79], v[48:51], v[16:31]
	v_mfma_f32_32x32x16_bf16 v[16:31], v[88:91], v[32:35], v[16:31]
	s_waitcnt vmcnt(0)
	v_mfma_f32_32x32x16_bf16 v[0:15], v[168:171], v[96:99], v[0:15]
	v_mfma_f32_32x32x16_bf16 v[0:15], v[172:175], v[84:87], v[0:15]
	v_mfma_f32_32x32x16_bf16 v[0:15], v[176:179], v[80:83], v[0:15]
	v_mfma_f32_32x32x16_bf16 v[0:15], v[180:183], v[64:67], v[0:15]
	v_mfma_f32_32x32x16_bf16 v[0:15], v[184:187], v[68:71], v[0:15]
	v_mfma_f32_32x32x16_bf16 v[0:15], v[188:191], v[52:55], v[0:15]
	v_mfma_f32_32x32x16_bf16 v[0:15], v[192:195], v[48:51], v[0:15]
	v_mfma_f32_32x32x16_bf16 v[0:15], v[196:199], v[32:35], v[0:15]
	s_addk_i32 s0, 0x100
	s_cmpk_eq_i32 s0, 0x400
	v_add_u32_e32 v131, 64, v131
	s_cbranch_scc0 .LBB0_308
	v_readlane_b32 s0, v251, 50
	v_bfe_u32 v230, v206, 6, 2
	v_lshlrev_b32_e32 v231, 2, v165
	v_add_u32_e32 v232, s0, v166
	v_readlane_b32 s0, v251, 53
	v_lshl_or_b32 v232, v232, 6, v231
	v_lshlrev_b32_e32 v230, 5, v230
	v_readlane_b32 s2, v251, 56
	v_or3_b32 v230, v230, s0, v164
	v_readlane_b32 s0, v253, 59
	v_lshlrev_b32_e32 v128, 1, v230
	v_readlane_b32 s1, v253, 60
	v_ashrrev_i32_e32 v233, 31, v232
	v_readlane_b32 s3, v251, 57
	v_lshl_add_u64 v[228:229], s[0:1], 0, v[128:129]
	s_movk_i32 s4, 0x3800
	v_lshl_add_u64 v[232:233], s[2:3], 0, v[232:233]
	v_mad_u64_u32 v[226:227], s[0:1], v232, s4, v[228:229]
	v_mad_i32_i24 v227, v233, s4, v227
	global_load_ushort v167, v[226:227], off offset:1024
	s_mov_b64 s[0:1], 0x3800
	v_lshl_add_u64 v[220:221], v[226:227], 0, s[0:1]
	global_load_ushort v168, v[220:221], off offset:1024
	s_mov_b64 s[0:1], 0x7000
	v_lshl_add_u64 v[222:223], v[226:227], 0, s[0:1]
	global_load_ushort v169, v[222:223], off offset:1024
	s_mov_b64 s[0:1], 0xa800
	v_lshl_add_u64 v[224:225], v[226:227], 0, s[0:1]
	global_load_ushort v170, v[224:225], off offset:1024
	s_mov_b64 s[0:1], 0x1c000
	v_lshl_add_u64 v[218:219], v[226:227], 0, s[0:1]
	global_load_ushort v171, v[218:219], off offset:1024
	s_mov_b64 s[0:1], 0x1f800
	v_lshl_add_u64 v[220:221], v[226:227], 0, s[0:1]
	global_load_ushort v172, v[220:221], off offset:1024
	s_mov_b64 s[0:1], 0x23000
	v_lshl_add_u64 v[222:223], v[226:227], 0, s[0:1]
	global_load_ushort v173, v[222:223], off offset:1024
	s_mov_b64 s[0:1], 0x26800
	v_lshl_add_u64 v[224:225], v[226:227], 0, s[0:1]
	global_load_ushort v174, v[224:225], off offset:1024
	s_mov_b64 s[0:1], 0x38000
	v_lshl_add_u64 v[218:219], v[226:227], 0, s[0:1]
	global_load_ushort v175, v[218:219], off offset:1024
	s_mov_b64 s[0:1], 0x3b800
	v_lshl_add_u64 v[220:221], v[226:227], 0, s[0:1]
	global_load_ushort v176, v[220:221], off offset:1024
	s_mov_b64 s[0:1], 0x3f000
	v_lshl_add_u64 v[222:223], v[226:227], 0, s[0:1]
	global_load_ushort v177, v[222:223], off offset:1024
	s_mov_b64 s[0:1], 0x42800
	v_lshl_add_u64 v[224:225], v[226:227], 0, s[0:1]
	global_load_ushort v178, v[224:225], off offset:1024
	s_mov_b64 s[0:1], 0x54000
	v_lshl_add_u64 v[218:219], v[226:227], 0, s[0:1]
	global_load_ushort v179, v[218:219], off offset:1024
	s_mov_b64 s[0:1], 0x57800
	v_lshl_add_u64 v[220:221], v[226:227], 0, s[0:1]
	global_load_ushort v180, v[220:221], off offset:1024
	s_mov_b64 s[0:1], 0x5b000
	v_lshl_add_u64 v[222:223], v[226:227], 0, s[0:1]
	global_load_ushort v181, v[222:223], off offset:1024
	s_mov_b64 s[0:1], 0x5e800
	v_lshl_add_u64 v[224:225], v[226:227], 0, s[0:1]
	global_load_ushort v182, v[224:225], off offset:1024
	s_mov_b64 s[0:1], 0x70000
	v_lshl_add_u64 v[218:219], v[226:227], 0, s[0:1]
	global_load_ushort v183, v[218:219], off offset:1024
	s_mov_b64 s[0:1], 0x73800
	v_lshl_add_u64 v[220:221], v[226:227], 0, s[0:1]
	global_load_ushort v184, v[220:221], off offset:1024
	s_mov_b64 s[0:1], 0x77000
	v_lshl_add_u64 v[222:223], v[226:227], 0, s[0:1]
	global_load_ushort v185, v[222:223], off offset:1024
	s_mov_b64 s[0:1], 0x7a800
	v_lshl_add_u64 v[224:225], v[226:227], 0, s[0:1]
	global_load_ushort v186, v[224:225], off offset:1024
	s_mov_b64 s[0:1], 0x8c000
	v_lshl_add_u64 v[218:219], v[226:227], 0, s[0:1]
	global_load_ushort v187, v[218:219], off offset:1024
	s_mov_b64 s[0:1], 0x8f800
	v_lshl_add_u64 v[220:221], v[226:227], 0, s[0:1]
	global_load_ushort v188, v[220:221], off offset:1024
	s_mov_b64 s[0:1], 0x93000
	v_lshl_add_u64 v[222:223], v[226:227], 0, s[0:1]
	global_load_ushort v189, v[222:223], off offset:1024
	s_mov_b64 s[0:1], 0x96800
	v_lshl_add_u64 v[224:225], v[226:227], 0, s[0:1]
	global_load_ushort v190, v[224:225], off offset:1024
	s_mov_b64 s[0:1], 0xa8000
	v_lshl_add_u64 v[218:219], v[226:227], 0, s[0:1]
	global_load_ushort v191, v[218:219], off offset:1024
	s_mov_b64 s[0:1], 0xab800
	v_lshl_add_u64 v[220:221], v[226:227], 0, s[0:1]
	global_load_ushort v192, v[220:221], off offset:1024
	s_mov_b64 s[0:1], 0xaf000
	v_lshl_add_u64 v[222:223], v[226:227], 0, s[0:1]
	global_load_ushort v193, v[222:223], off offset:1024
	s_mov_b64 s[0:1], 0xb2800
	v_lshl_add_u64 v[224:225], v[226:227], 0, s[0:1]
	global_load_ushort v194, v[224:225], off offset:1024
	s_mov_b64 s[0:1], 0xc4000
	v_lshl_add_u64 v[218:219], v[226:227], 0, s[0:1]
	global_load_ushort v195, v[218:219], off offset:1024
	s_mov_b64 s[0:1], 0xc7800
	v_lshl_add_u64 v[220:221], v[226:227], 0, s[0:1]
	global_load_ushort v196, v[220:221], off offset:1024
	s_mov_b64 s[0:1], 0xcb000
	v_lshl_add_u64 v[222:223], v[226:227], 0, s[0:1]
	global_load_ushort v197, v[222:223], off offset:1024
	s_mov_b64 s[0:1], 0xce800
	v_lshl_add_u64 v[224:225], v[226:227], 0, s[0:1]
	global_load_ushort v198, v[224:225], off offset:1024
	v_readlane_b32 s0, v251, 25
	v_readlane_b32 s1, v251, 26
	v_lshlrev_b32_e32 v128, 1, v230
	v_lshlrev_b64 v[224:225], 10, v[232:233]
	v_lshl_add_u64 v[228:229], s[0:1], 0, v[128:129]
	v_lshl_add_u64 v[228:229], v[228:229], 0, v[224:225]
	s_waitcnt vmcnt(0)
	v_lshlrev_b32_e32 v167, 16, v167
	v_mul_f32_e32 v207, 0xbfb8aa3b, v167
	v_exp_f32_e32 v207, v207
	v_lshlrev_b32_e32 v168, 16, v168
	v_mul_f32_e32 v208, 0xbfb8aa3b, v168
	v_exp_f32_e32 v208, v208
	v_lshlrev_b32_e32 v169, 16, v169
	v_mul_f32_e32 v209, 0xbfb8aa3b, v169
	v_exp_f32_e32 v209, v209
	v_lshlrev_b32_e32 v170, 16, v170
	v_mul_f32_e32 v210, 0xbfb8aa3b, v170
	v_exp_f32_e32 v210, v210
	v_lshlrev_b32_e32 v171, 16, v171
	v_mul_f32_e32 v211, 0xbfb8aa3b, v171
	v_exp_f32_e32 v211, v211
	v_lshlrev_b32_e32 v172, 16, v172
	v_mul_f32_e32 v212, 0xbfb8aa3b, v172
	v_exp_f32_e32 v212, v212
	v_lshlrev_b32_e32 v173, 16, v173
	v_mul_f32_e32 v213, 0xbfb8aa3b, v173
	v_exp_f32_e32 v213, v213
	v_lshlrev_b32_e32 v174, 16, v174
	v_mul_f32_e32 v214, 0xbfb8aa3b, v174
	v_exp_f32_e32 v214, v214
	v_lshlrev_b32_e32 v175, 16, v175
	v_mul_f32_e32 v215, 0xbfb8aa3b, v175
	v_exp_f32_e32 v215, v215
	v_lshlrev_b32_e32 v176, 16, v176
	v_mul_f32_e32 v216, 0xbfb8aa3b, v176
	v_exp_f32_e32 v216, v216
	v_lshlrev_b32_e32 v177, 16, v177
	v_mul_f32_e32 v217, 0xbfb8aa3b, v177
	v_exp_f32_e32 v217, v217
	v_lshlrev_b32_e32 v178, 16, v178
	v_mul_f32_e32 v218, 0xbfb8aa3b, v178
	v_exp_f32_e32 v218, v218
	v_lshlrev_b32_e32 v179, 16, v179
	v_mul_f32_e32 v219, 0xbfb8aa3b, v179
	v_exp_f32_e32 v219, v219
	v_lshlrev_b32_e32 v180, 16, v180
	v_mul_f32_e32 v220, 0xbfb8aa3b, v180
	v_exp_f32_e32 v220, v220
	v_lshlrev_b32_e32 v181, 16, v181
	v_mul_f32_e32 v221, 0xbfb8aa3b, v181
	v_exp_f32_e32 v221, v221
	v_lshlrev_b32_e32 v182, 16, v182
	v_mul_f32_e32 v222, 0xbfb8aa3b, v182
	v_exp_f32_e32 v222, v222
	s_nop 0
	v_add_f32_e32 v207, 1.0, v207
	v_add_f32_e32 v208, 1.0, v208
	v_add_f32_e32 v209, 1.0, v209
	v_add_f32_e32 v210, 1.0, v210
	v_add_f32_e32 v211, 1.0, v211
	v_add_f32_e32 v212, 1.0, v212
	v_add_f32_e32 v213, 1.0, v213
	v_add_f32_e32 v214, 1.0, v214
	v_add_f32_e32 v215, 1.0, v215
	v_add_f32_e32 v216, 1.0, v216
	v_add_f32_e32 v217, 1.0, v217
	v_add_f32_e32 v218, 1.0, v218
	v_add_f32_e32 v219, 1.0, v219
	v_add_f32_e32 v220, 1.0, v220
	v_add_f32_e32 v221, 1.0, v221
	v_add_f32_e32 v222, 1.0, v222
	v_rcp_f32_e32 v207, v207
	v_rcp_f32_e32 v208, v208
	v_rcp_f32_e32 v209, v209
	v_rcp_f32_e32 v210, v210
	v_rcp_f32_e32 v211, v211
	v_rcp_f32_e32 v212, v212
	v_rcp_f32_e32 v213, v213
	v_rcp_f32_e32 v214, v214
	v_rcp_f32_e32 v215, v215
	v_rcp_f32_e32 v216, v216
	v_rcp_f32_e32 v217, v217
	v_rcp_f32_e32 v218, v218
	v_rcp_f32_e32 v219, v219
	v_rcp_f32_e32 v220, v220
	v_rcp_f32_e32 v221, v221
	v_rcp_f32_e32 v222, v222
	s_nop 0
	v_mul_f32_e32 v167, v207, v167
	v_mul_f32_e32 v168, v208, v168
	v_mul_f32_e32 v169, v209, v169
	v_mul_f32_e32 v170, v210, v170
	v_mul_f32_e32 v171, v211, v171
	v_mul_f32_e32 v172, v212, v172
	v_mul_f32_e32 v173, v213, v173
	v_mul_f32_e32 v174, v214, v174
	v_mul_f32_e32 v175, v215, v175
	v_mul_f32_e32 v176, v216, v176
	v_mul_f32_e32 v177, v217, v177
	v_mul_f32_e32 v178, v218, v178
	v_mul_f32_e32 v179, v219, v179
	v_mul_f32_e32 v180, v220, v180
	v_mul_f32_e32 v181, v221, v181
	v_mul_f32_e32 v182, v222, v182
	v_lshlrev_b32_e32 v183, 16, v183
	v_mul_f32_e32 v207, 0xbfb8aa3b, v183
	v_exp_f32_e32 v207, v207
	v_lshlrev_b32_e32 v184, 16, v184
	v_mul_f32_e32 v208, 0xbfb8aa3b, v184
	v_exp_f32_e32 v208, v208
	v_lshlrev_b32_e32 v185, 16, v185
	v_mul_f32_e32 v209, 0xbfb8aa3b, v185
	v_exp_f32_e32 v209, v209
	v_lshlrev_b32_e32 v186, 16, v186
	v_mul_f32_e32 v210, 0xbfb8aa3b, v186
	v_exp_f32_e32 v210, v210
	v_lshlrev_b32_e32 v187, 16, v187
	v_mul_f32_e32 v211, 0xbfb8aa3b, v187
	v_exp_f32_e32 v211, v211
	v_lshlrev_b32_e32 v188, 16, v188
	v_mul_f32_e32 v212, 0xbfb8aa3b, v188
	v_exp_f32_e32 v212, v212
	v_lshlrev_b32_e32 v189, 16, v189
	v_mul_f32_e32 v213, 0xbfb8aa3b, v189
	v_exp_f32_e32 v213, v213
	v_lshlrev_b32_e32 v190, 16, v190
	v_mul_f32_e32 v214, 0xbfb8aa3b, v190
	v_exp_f32_e32 v214, v214
	v_lshlrev_b32_e32 v191, 16, v191
	v_mul_f32_e32 v215, 0xbfb8aa3b, v191
	v_exp_f32_e32 v215, v215
	v_lshlrev_b32_e32 v192, 16, v192
	v_mul_f32_e32 v216, 0xbfb8aa3b, v192
	v_exp_f32_e32 v216, v216
	v_lshlrev_b32_e32 v193, 16, v193
	v_mul_f32_e32 v217, 0xbfb8aa3b, v193
	v_exp_f32_e32 v217, v217
	v_lshlrev_b32_e32 v194, 16, v194
	v_mul_f32_e32 v218, 0xbfb8aa3b, v194
	v_exp_f32_e32 v218, v218
	v_lshlrev_b32_e32 v195, 16, v195
	v_mul_f32_e32 v219, 0xbfb8aa3b, v195
	v_exp_f32_e32 v219, v219
	v_lshlrev_b32_e32 v196, 16, v196
	v_mul_f32_e32 v220, 0xbfb8aa3b, v196
	v_exp_f32_e32 v220, v220
	v_lshlrev_b32_e32 v197, 16, v197
	v_mul_f32_e32 v221, 0xbfb8aa3b, v197
	v_exp_f32_e32 v221, v221
	v_lshlrev_b32_e32 v198, 16, v198
	v_mul_f32_e32 v222, 0xbfb8aa3b, v198
	v_exp_f32_e32 v222, v222
	s_nop 0
	v_add_f32_e32 v207, 1.0, v207
	v_add_f32_e32 v208, 1.0, v208
	v_add_f32_e32 v209, 1.0, v209
	v_add_f32_e32 v210, 1.0, v210
	v_add_f32_e32 v211, 1.0, v211
	v_add_f32_e32 v212, 1.0, v212
	v_add_f32_e32 v213, 1.0, v213
	v_add_f32_e32 v214, 1.0, v214
	v_add_f32_e32 v215, 1.0, v215
	v_add_f32_e32 v216, 1.0, v216
	v_add_f32_e32 v217, 1.0, v217
	v_add_f32_e32 v218, 1.0, v218
	v_add_f32_e32 v219, 1.0, v219
	v_add_f32_e32 v220, 1.0, v220
	v_add_f32_e32 v221, 1.0, v221
	v_add_f32_e32 v222, 1.0, v222
	v_rcp_f32_e32 v207, v207
	v_rcp_f32_e32 v208, v208
	v_rcp_f32_e32 v209, v209
	v_rcp_f32_e32 v210, v210
	v_rcp_f32_e32 v211, v211
	v_rcp_f32_e32 v212, v212
	v_rcp_f32_e32 v213, v213
	v_rcp_f32_e32 v214, v214
	v_rcp_f32_e32 v215, v215
	v_rcp_f32_e32 v216, v216
	v_rcp_f32_e32 v217, v217
	v_rcp_f32_e32 v218, v218
	v_rcp_f32_e32 v219, v219
	v_rcp_f32_e32 v220, v220
	v_rcp_f32_e32 v221, v221
	v_rcp_f32_e32 v222, v222
	s_nop 0
	v_mul_f32_e32 v183, v207, v183
	v_mul_f32_e32 v184, v208, v184
	v_mul_f32_e32 v185, v209, v185
	v_mul_f32_e32 v186, v210, v186
	v_mul_f32_e32 v187, v211, v187
	v_mul_f32_e32 v188, v212, v188
	v_mul_f32_e32 v189, v213, v189
	v_mul_f32_e32 v190, v214, v190
	v_mul_f32_e32 v191, v215, v191
	v_mul_f32_e32 v192, v216, v192
	v_mul_f32_e32 v193, v217, v193
	v_mul_f32_e32 v194, v218, v194
	v_mul_f32_e32 v195, v219, v195
	v_mul_f32_e32 v196, v220, v196
	v_mul_f32_e32 v197, v221, v197
	v_mul_f32_e32 v198, v222, v198
	v_mul_f32_e32 v16, 0x3bb504f3, v16
	v_mul_f32_e32 v17, 0x3bb504f3, v17
	v_mul_f32_e32 v18, 0x3bb504f3, v18
	v_mul_f32_e32 v19, 0x3bb504f3, v19
	v_mul_f32_e32 v20, 0x3bb504f3, v20
	v_mul_f32_e32 v21, 0x3bb504f3, v21
	v_mul_f32_e32 v22, 0x3bb504f3, v22
	v_mul_f32_e32 v23, 0x3bb504f3, v23
	v_mul_f32_e32 v24, 0x3bb504f3, v24
	v_mul_f32_e32 v25, 0x3bb504f3, v25
	v_mul_f32_e32 v26, 0x3bb504f3, v26
	v_mul_f32_e32 v27, 0x3bb504f3, v27
	v_mul_f32_e32 v28, 0x3bb504f3, v28
	v_mul_f32_e32 v29, 0x3bb504f3, v29
	v_mul_f32_e32 v30, 0x3bb504f3, v30
	v_mul_f32_e32 v31, 0x3bb504f3, v31
	v_mul_f32_e32 v0, 0x3bb504f3, v0
	v_mul_f32_e32 v1, 0x3bb504f3, v1
	v_mul_f32_e32 v2, 0x3bb504f3, v2
	v_mul_f32_e32 v3, 0x3bb504f3, v3
	v_mul_f32_e32 v4, 0x3bb504f3, v4
	v_mul_f32_e32 v5, 0x3bb504f3, v5
	v_mul_f32_e32 v6, 0x3bb504f3, v6
	v_mul_f32_e32 v7, 0x3bb504f3, v7
	v_mul_f32_e32 v8, 0x3bb504f3, v8
	v_mul_f32_e32 v9, 0x3bb504f3, v9
	v_mul_f32_e32 v10, 0x3bb504f3, v10
	v_mul_f32_e32 v11, 0x3bb504f3, v11
	v_mul_f32_e32 v12, 0x3bb504f3, v12
	v_mul_f32_e32 v13, 0x3bb504f3, v13
	v_mul_f32_e32 v14, 0x3bb504f3, v14
	v_mul_f32_e32 v15, 0x3bb504f3, v15
	v_mul_f32_e32 v16, v16, v167
	v_mul_f32_e32 v17, v17, v168
	v_mul_f32_e32 v18, v18, v169
	v_mul_f32_e32 v19, v19, v170
	v_mul_f32_e32 v20, v20, v171
	v_mul_f32_e32 v21, v21, v172
	v_mul_f32_e32 v22, v22, v173
	v_mul_f32_e32 v23, v23, v174
	v_mul_f32_e32 v24, v24, v175
	v_mul_f32_e32 v25, v25, v176
	v_mul_f32_e32 v26, v26, v177
	v_mul_f32_e32 v27, v27, v178
	v_mul_f32_e32 v28, v28, v179
	v_mul_f32_e32 v29, v29, v180
	v_mul_f32_e32 v30, v30, v181
	v_mul_f32_e32 v31, v31, v182
	v_mul_f32_e32 v0, v0, v183
	v_mul_f32_e32 v1, v1, v184
	v_mul_f32_e32 v2, v2, v185
	v_mul_f32_e32 v3, v3, v186
	v_mul_f32_e32 v4, v4, v187
	v_mul_f32_e32 v5, v5, v188
	v_mul_f32_e32 v6, v6, v189
	v_mul_f32_e32 v7, v7, v190
	v_mul_f32_e32 v8, v8, v191
	v_mul_f32_e32 v9, v9, v192
	v_mul_f32_e32 v10, v10, v193
	v_mul_f32_e32 v11, v11, v194
	v_mul_f32_e32 v12, v12, v195
	v_mul_f32_e32 v13, v13, v196
	v_mul_f32_e32 v14, v14, v197
	v_mul_f32_e32 v15, v15, v198
	v_cvt_pk_bf16_f32 v207, v16, v17
	v_mov_b64_e32 v[216:217], v[228:229]
	global_store_short v[216:217], v207, off
	global_store_short_d16_hi v[216:217], v207, off offset:1024
	v_cvt_pk_bf16_f32 v208, v18, v19
	s_mov_b64 s[0:1], 0x800
	v_lshl_add_u64 v[218:219], v[228:229], 0, s[0:1]
	global_store_short v[218:219], v208, off
	global_store_short_d16_hi v[218:219], v208, off offset:1024
	v_cvt_pk_bf16_f32 v209, v20, v21
	s_mov_b64 s[0:1], 0x2000
	v_lshl_add_u64 v[220:221], v[228:229], 0, s[0:1]
	global_store_short v[220:221], v209, off
	global_store_short_d16_hi v[220:221], v209, off offset:1024
	v_cvt_pk_bf16_f32 v210, v22, v23
	s_mov_b64 s[0:1], 0x2800
	v_lshl_add_u64 v[222:223], v[228:229], 0, s[0:1]
	global_store_short v[222:223], v210, off
	global_store_short_d16_hi v[222:223], v210, off offset:1024
	v_cvt_pk_bf16_f32 v211, v24, v25
	s_mov_b64 s[0:1], 0x4000
	v_lshl_add_u64 v[216:217], v[228:229], 0, s[0:1]
	global_store_short v[216:217], v211, off
	global_store_short_d16_hi v[216:217], v211, off offset:1024
	v_cvt_pk_bf16_f32 v212, v26, v27
	s_mov_b64 s[0:1], 0x4800
	v_lshl_add_u64 v[218:219], v[228:229], 0, s[0:1]
	global_store_short v[218:219], v212, off
	global_store_short_d16_hi v[218:219], v212, off offset:1024
	v_cvt_pk_bf16_f32 v213, v28, v29
	s_mov_b64 s[0:1], 0x6000
	v_lshl_add_u64 v[220:221], v[228:229], 0, s[0:1]
	global_store_short v[220:221], v213, off
	global_store_short_d16_hi v[220:221], v213, off offset:1024
	v_cvt_pk_bf16_f32 v214, v30, v31
	s_mov_b64 s[0:1], 0x6800
	v_lshl_add_u64 v[222:223], v[228:229], 0, s[0:1]
	global_store_short v[222:223], v214, off
	global_store_short_d16_hi v[222:223], v214, off offset:1024
	v_cvt_pk_bf16_f32 v207, v0, v1
	s_mov_b64 s[0:1], 0x8000
	v_lshl_add_u64 v[216:217], v[228:229], 0, s[0:1]
	global_store_short v[216:217], v207, off
	global_store_short_d16_hi v[216:217], v207, off offset:1024
	v_cvt_pk_bf16_f32 v208, v2, v3
	s_mov_b64 s[0:1], 0x8800
	v_lshl_add_u64 v[218:219], v[228:229], 0, s[0:1]
	global_store_short v[218:219], v208, off
	global_store_short_d16_hi v[218:219], v208, off offset:1024
	v_cvt_pk_bf16_f32 v209, v4, v5
	s_mov_b64 s[0:1], 0xa000
	v_lshl_add_u64 v[220:221], v[228:229], 0, s[0:1]
	global_store_short v[220:221], v209, off
	global_store_short_d16_hi v[220:221], v209, off offset:1024
	v_cvt_pk_bf16_f32 v210, v6, v7
	s_mov_b64 s[0:1], 0xa800
	v_lshl_add_u64 v[222:223], v[228:229], 0, s[0:1]
	global_store_short v[222:223], v210, off
	global_store_short_d16_hi v[222:223], v210, off offset:1024
	v_cvt_pk_bf16_f32 v211, v8, v9
	s_mov_b64 s[0:1], 0xc000
	v_lshl_add_u64 v[216:217], v[228:229], 0, s[0:1]
	global_store_short v[216:217], v211, off
	global_store_short_d16_hi v[216:217], v211, off offset:1024
	v_cvt_pk_bf16_f32 v212, v10, v11
	s_mov_b64 s[0:1], 0xc800
	v_lshl_add_u64 v[218:219], v[228:229], 0, s[0:1]
	global_store_short v[218:219], v212, off
	global_store_short_d16_hi v[218:219], v212, off offset:1024
	v_cvt_pk_bf16_f32 v213, v12, v13
	s_mov_b64 s[0:1], 0xe000
	v_lshl_add_u64 v[220:221], v[228:229], 0, s[0:1]
	global_store_short v[220:221], v213, off
	global_store_short_d16_hi v[220:221], v213, off offset:1024
	v_cvt_pk_bf16_f32 v214, v14, v15
	s_mov_b64 s[0:1], 0xe800
	v_lshl_add_u64 v[222:223], v[228:229], 0, s[0:1]
	global_store_short v[222:223], v214, off
	global_store_short_d16_hi v[222:223], v214, off offset:1024
